# branch B: q fragments of unit u+1 loaded one unit ahead (sliding mode), no per-unit wait on q
# baseline (speedup 1.0000x reference)
; __device__ __forceinline__ void attn_b_unit(LAS unsigned char* lds, const bf16* Z, bf16* Y, int unit) {
;     const int tid = threadIdx.x, lane = tid & 63, wid = tid >> 6, lq = lane & 15, g = lane >> 4;
;     const int rp = unit & 63, h = (unit >> 6) & 7, b = unit >> 9;
;     const size_t tok0 = (size_t)b * SEQ;
;     const int R0 = clampi(2 * rp - 4, 0, 120);
;     LAS unsigned char* Kl = lds + B_KOFF; LAS unsigned char* Vl = lds + B_VOFF; LAS float* T = (LAS float*)(lds + B_TOFF);
;     const int rq = 2 * rp + (wid >> 2), cb = wid & 3, c = 16 * cb + lq;
;     const int r0q = clampi(rq - 4, 0, 120), kc0 = clampi(16 * cb - 8, 0, 32), cs = clampi(c - 8, 0, 48);
;     const size_t qtok = tok0 + (size_t)rq * 64 + c;
;     const unsigned char* qp = (const unsigned char*)Z + tmo((int)qtok, Z_QB / 64 + h, ZLD / 64) + 16 * g;
;     const bf16x8 qf0 = *(const bf16x8*)qp, qf1 = *(const bf16x8*)(qp + 64);
;     float m0 = -1e30f, l0 = 0.f, m1 = -1e30f, l1 = 0.f;
;     f32x4 O0[4], O1[4];
; #pragma unroll
;     for (int d = 0; d < 4; ++d) { O0[d] = (f32x4){0.f, 0.f, 0.f, 0.f}; O1[d] = (f32x4){0.f, 0.f, 0.f, 0.f}; }
;     const int kcl = kc0 + 4 * g;
;     const int tb = 16 + (kcl - c + 15);
;     const int Rb = (r0q - R0) * 64 + kc0;
;     const LAS unsigned char* kp0 = Kl + swz(Rb + lq, g); const LAS unsigned char* kp1 = Kl + swz(Rb + lq, 4 + g);
;     const LAS unsigned char* vp[4];
;     { const int i = lane & 15, rq4 = i >> 2, p = i & 3;
; #pragma unroll
;       for (int db = 0; db < 4; ++db) vp[db] = Vl + swz(Rb + 4 * g + rq4, 2 * db + (p >> 1)) + 8 * (p & 1); }
;     const LAS float* T0 = T + tb + (r0q - rq + 7) * 32;
;     const LAS float* tpa[4]; const LAS float* tpb[4];
; #pragma unroll
;     for (int r = 0; r < 4; ++r) { const int kca = kcl + r, kcb = kca + 16;
;         tpa[r] = (kca >= cs && kca <= cs + 15) ? T0 + r : T + B_TREAL; tpb[r] = (kcb >= cs && kcb <= cs + 15) ? T0 + 16 + r : T + B_TREAL; }
; __global__ void __launch_bounds__(NTHREADS, 2) mk_fwd(Args args) {
;     ...
;             v4u kr[9], vr[9]; float tr[2]; int u = vcu; const int NU = BATCH * 8 * 64;
;             if (u < NU) attn_b_prefetch(Zb, rpb, u, kr, vr, tr);
;             for (; u < NU; u += G) {
;                 attn_b_commit(lds, kr, vr, tr);
;                 __syncthreads();
;                 if (u + G < NU) attn_b_prefetch(Zb, rpb, u + G, kr, vr, tr);
.LBB0_278:
	s_or_b64 exec, exec, s[10:11]
	v_lshlrev_b32_e32 v79, 7, v78
	v_xor_b32_e32 v78, v78, v218
	v_lshlrev_b32_e32 v78, 4, v78
	s_movk_i32 s0, 0x70
	v_and_or_b32 v78, v78, s0, v79
	v_add_u32_e32 v79, 0x200, v218
	v_add_u32_e32 v82, 0x600, v218
	v_add_u32_e32 v84, 0xa00, v218
	v_add_u32_e32 v86, 0xe00, v218
	v_lshrrev_b32_e32 v80, 3, v79
	v_lshrrev_b32_e32 v82, 3, v82
	v_lshrrev_b32_e32 v84, 3, v84
	v_lshrrev_b32_e32 v86, 3, v86
	v_lshlrev_b32_e32 v81, 7, v80
	v_xor_b32_e32 v80, v80, v218
	v_lshlrev_b32_e32 v83, 7, v82
	v_xor_b32_e32 v82, v82, v218
	v_lshlrev_b32_e32 v85, 7, v84
	v_xor_b32_e32 v84, v84, v218
	v_lshlrev_b32_e32 v87, 7, v86
	v_xor_b32_e32 v86, v86, v218
	v_lshlrev_b32_e32 v80, 4, v80
	v_lshlrev_b32_e32 v82, 4, v82
	v_lshlrev_b32_e32 v84, 4, v84
	v_lshlrev_b32_e32 v86, 4, v86
	v_mad_i32_i24 v112, v61, 31, v59
	v_lshrrev_b32_e32 v59, 2, v218
	v_and_or_b32 v80, v80, s0, v81
	v_and_or_b32 v82, v82, s0, v83
	v_and_or_b32 v84, v84, s0, v85
	v_and_or_b32 v86, v86, s0, v87
	s_movk_i32 s0, 0x320
	v_cmp_eq_u32_e64 s[8:9], 15, v60
	v_and_b32_e32 v60, 48, v59
	v_cmp_lt_u32_e64 s[4:5], 31, v218
	v_cmp_gt_u32_e64 s[22:23], s0, v218
	s_movk_i32 s0, 0x120
	v_cmp_lt_i32_e64 s[6:7], 14, v61
	v_add_u32_e32 v59, -8, v60
	v_cndmask_b32_e64 v108, 0, v58, s[4:5]
	v_cmp_gt_u32_e64 s[4:5], s0, v218
	s_or_b64 s[0:1], s[8:9], s[6:7]
	v_and_b32_e32 v113, 15, v218
	v_bfe_u32 v114, v218, 4, 2
	v_min_u32_e32 v61, 32, v59
	v_cmp_ne_u32_e64 s[8:9], 0, v60
	v_or_b32_e32 v116, v60, v113
	v_lshlrev_b32_e32 v60, 2, v114
	v_cndmask_b32_e64 v117, 0, v61, s[8:9]
	v_bfe_u32 v87, v218, 2, 2
	s_add_i32 s3, 0, 0x24000
	v_subrev_co_u32_e64 v59, s[6:7], 8, v116
	v_add_u32_e32 v61, v117, v60
	v_or_b32_e32 v119, v60, v87
	v_lshlrev_b32_e32 v60, 3, v218
	v_lshl_add_u32 v111, v79, 2, s3
	s_xor_b64 s[28:29], s[0:1], -1
	v_min_u32_e32 v79, 48, v59
	v_and_b32_e32 v60, 8, v60
	s_add_i32 s0, 0, 0x12000
	v_add_u32_e32 v120, s0, v60
	v_cndmask_b32_e64 v60, v79, 0, s[6:7]
	v_sub_u32_e32 v79, v61, v116
	v_lshl_add_u32 v121, v79, 2, s3
	v_add_u32_e32 v79, 15, v60
	v_add_u32_e32 v87, 16, v61
	v_cmp_lt_u32_e64 s[6:7], v61, v60
	v_cmp_gt_u32_e64 s[8:9], v61, v79
	s_or_b64 s[6:7], s[6:7], s[8:9]
	v_cmp_lt_u32_e64 s[8:9], v87, v60
	v_cmp_gt_u32_e64 s[10:11], v87, v79
	v_or_b32_e32 v87, 1, v61
	s_or_b64 s[8:9], s[8:9], s[10:11]
	v_add_u32_e32 v88, 17, v61
	v_cmp_lt_u32_e64 s[10:11], v87, v60
	v_cmp_ge_u32_e64 s[12:13], v61, v79
	s_or_b64 s[10:11], s[10:11], s[12:13]
	v_cmp_lt_u32_e64 s[12:13], v88, v60
	v_cmp_gt_u32_e64 s[14:15], v88, v79
	v_or_b32_e32 v87, 2, v61
	s_or_b64 s[12:13], s[12:13], s[14:15]
	v_add_u32_e32 v88, 18, v61
	v_cmp_lt_u32_e64 s[14:15], v87, v60
	v_cmp_gt_u32_e64 s[16:17], v87, v79
	s_or_b64 s[14:15], s[14:15], s[16:17]
	v_cmp_lt_u32_e64 s[16:17], v88, v60
	v_cmp_gt_u32_e64 s[18:19], v88, v79
	v_or_b32_e32 v87, 3, v61
	s_or_b64 s[16:17], s[16:17], s[18:19]
	v_add_u32_e32 v61, 19, v61
	v_cmp_lt_u32_e64 s[18:19], v87, v60
	v_cmp_gt_u32_e64 s[20:21], v87, v79
	s_or_b64 s[18:19], s[18:19], s[20:21]
	v_cmp_lt_u32_e64 s[20:21], v61, v60
	v_cmp_gt_u32_e64 s[24:25], v61, v79
	v_add_u32_e32 v60, 0xfffffde0, v218
	s_movk_i32 s1, 0xfdef
	v_or_b32_e32 v81, 0x4000, v78
	v_or_b32_e32 v83, 0x8000, v78
	v_or_b32_e32 v85, 0xc000, v78
	v_or_b32_e32 v109, 0x10000, v78
	v_mov_b32_e32 v59, 0
	s_or_b64 s[20:21], s[20:21], s[24:25]
	v_cmp_lt_u32_e64 s[24:25], s1, v60
	s_mov_b32 s27, 0
	v_lshl_add_u32 v110, v218, 2, s3
	v_lshrrev_b32_e32 v115, 8, v218
	v_lshlrev_b32_e32 v104, 4, v114
	v_mov_b32_e32 v105, v59
	v_or_b32_e32 v118, 4, v114
	s_and_b64 s[24:25], s[24:25], s[28:29]
	v_cndmask_b32_e32 v122, 0, v58, vcc
	s_lshl_b32 s1, s90, 4
	s_lshl_b32 s3, s90, 1
	v_add_u32_e32 v123, 0, v78
	v_add_u32_e32 v124, s0, v78
	v_add_u32_e32 v125, 0, v80
	v_add_u32_e32 v126, s0, v80
	v_add_u32_e32 v127, s0, v81
	v_add_u32_e32 v128, 0, v82
	v_add_u32_e32 v129, s0, v82
	v_add_u32_e32 v130, s0, v83
	v_add_u32_e32 v131, 0, v84
	v_add_u32_e32 v132, s0, v84
	v_add_u32_e32 v133, s0, v85
	v_add_u32_e32 v138, 0, v86
	v_add_u32_e32 v139, s0, v86
	v_add_u32_e32 v140, 0, v109
	s_movk_i32 s52, 0x79
	s_add_i32 s53, 0, 0x24880
	s_mov_b32 s54, 0xf149f2ca
	s_mov_b64 s[28:29], 0x40000
	s_mov_b32 s72, s89
	s_mov_b32 s85, 0
	s_mov_b32 s88, 1
	s_mov_b32 s32, 0
	s_branch .LBB0_281
.Lb_nonext:
	s_cmp_lg_u32 s91, 0
	s_cbranch_scc1 .Lb_q_skip
	s_waitcnt vmcnt(0)
.Lb_q_skip:
	s_branch .LBB0_280
.LBB0_279:
	s_or_b64 exec, exec, s[50:51]
; #define LAS __attribute__((address_space(3)))
; __device__ __forceinline__ size_t tmo(int row, int ct, int nct) { return ((size_t)(row >> 8) * nct + ct) * 32768 + (size_t)(row & 255) * 128; }
; __device__ __forceinline__ void attn_b_unit(LAS unsigned char* lds, const bf16* Z, bf16* Y, int unit) {
;     ...
;     const int R0 = clampi(2 * rp - 4, 0, 120);
;     LAS unsigned char* Kl = lds + B_KOFF; LAS unsigned char* Vl = lds + B_VOFF; LAS float* T = (LAS float*)(lds + B_TOFF);
;     const int rq = 2 * rp + (wid >> 2), cb = wid & 3, c = 16 * cb + lq;
;     const int r0q = clampi(rq - 4, 0, 120), kc0 = clampi(16 * cb - 8, 0, 32), cs = clampi(c - 8, 0, 48);
;     const size_t qtok = tok0 + (size_t)rq * 64 + c;
;     const unsigned char* qp = (const unsigned char*)Z + tmo((int)qtok, Z_QB / 64 + h, ZLD / 64) + 16 * g;
;     const bf16x8 qf0 = *(const bf16x8*)qp, qf1 = *(const bf16x8*)(qp + 64);
;     float m0 = -1e30f, l0 = 0.f, m1 = -1e30f, l1 = 0.f;
;     f32x4 O0[4], O1[4];
; #pragma unroll
;     for (int d = 0; d < 4; ++d) { O0[d] = (f32x4){0.f, 0.f, 0.f, 0.f}; O1[d] = (f32x4){0.f, 0.f, 0.f, 0.f}; }
;     const int kcl = kc0 + 4 * g;
;     const int tb = 16 + (kcl - c + 15);
;     const int Rb = (r0q - R0) * 64 + kc0;
;     const LAS unsigned char* kp0 = Kl + swz(Rb + lq, g); const LAS unsigned char* kp1 = Kl + swz(Rb + lq, 4 + g);
;     const LAS unsigned char* vp[4];
;     { const int i = lane & 15, rq4 = i >> 2, p = i & 3;
; #pragma unroll
;       for (int db = 0; db < 4; ++db) vp[db] = Vl + swz(Rb + 4 * g + rq4, 2 * db + (p >> 1)) + 8 * (p & 1); }
;     const LAS float* T0 = T + tb + (r0q - rq + 7) * 32;
;     const LAS float* tpa[4]; const LAS float* tpb[4];
; #pragma unroll
;     for (int r = 0; r < 4; ++r) { const int kca = kcl + r, kcb = kca + 16;
;         tpa[r] = (kca >= cs && kca <= cs + 15) ? T0 + r : T + B_TREAL; tpb[r] = (kcb >= cs && kcb <= cs + 15) ? T0 + 16 + r : T + B_TREAL; }
; #pragma unroll
;     for (int st = 0; st < 4; ++st) {
;         const int offA = st * 8192, offB = offA + 4 * 8192;
;         f32x4 SA0, SA1, SB0, SB1;
;         qk_at(kp0, kp1, offA, qf0, qf1, SA0, SA1);
;         qk_at(kp0, kp1, offB, qf0, qf1, SB0, SB1);
; #pragma unroll
;         for (int r = 0; r < 4; ++r) {
;             SA0[r] += tpa[r][st * 32]; SA1[r] += tpb[r][st * 32]; SB0[r] += tpa[r][st * 32 + 128]; SB1[r] += tpb[r][st * 32 + 128];
;         }
.LBB0_280:
	v_readlane_b32 s26, v246, 7
	s_nop 3
	s_lshr_b32 s26, s26, 2
	s_and_b32 s51, s58, 0x7e
	s_add_i32 s50, s51, s26
	s_sub_i32 s73, s50, 4
	s_max_i32 s73, s73, 0
	s_min_i32 s73, s73, 0x78
	s_sub_i32 s74, s73, s50
	s_lshl_b32 s74, s74, 7
	s_sub_i32 s75, s73, s84
	s_mul_i32 s76, s75, 57
	s_lshr_b32 s76, s76, 9
	s_mul_i32 s76, s76, 9
	s_sub_i32 s75, s75, s76
	s_lshl_b32 s76, s75, 13
	s_add_i32 s77, s76, 0x2000
	s_cmp_eq_u32 s77, 0x12000
	s_cselect_b32 s77, 0, s77
	s_add_i32 s78, s77, 0x2000
	s_cmp_eq_u32 s78, 0x12000
	s_cselect_b32 s78, 0, s78
	s_add_i32 s79, s78, 0x2000
	s_cmp_eq_u32 s79, 0x12000
	s_cselect_b32 s79, 0, s79
	s_add_i32 s80, s79, 0x2000
	s_cmp_eq_u32 s80, 0x12000
	s_cselect_b32 s80, 0, s80
	s_add_i32 s81, s80, 0x2000
	s_cmp_eq_u32 s81, 0x12000
	s_cselect_b32 s81, 0, s81
	s_add_i32 s82, s81, 0x2000
	s_cmp_eq_u32 s82, 0x12000
	s_cselect_b32 s82, 0, s82
	s_add_i32 s83, s82, 0x2000
	s_cmp_eq_u32 s83, 0x12000
	s_cselect_b32 s83, 0, s83
	v_add_u32_e32 v61, s51, v115
	s_and_b32 s26, s59, 0xffffe000
	v_lshlrev_b32_e32 v58, 6, v61
	v_add_u32_e32 v60, s26, v58
	s_bfe_u32 s50, s72, 0x30006
	v_ashrrev_i32_e32 v60, 8, v60
	v_or_b32_e32 v58, v58, v116
	v_lshlrev_b32_e32 v58, 7, v58
	v_and_b32_e32 v58, 0x7f80, v58
	v_add_u32_e32 v101, v117, v113
	v_add_u32_e32 v216, v117, v119
	v_bitop3_b32 v100, v101, v114, 7 bitop3:0x6c
	v_lshlrev_b32_e32 v217, 7, v101
	v_lshlrev_b32_e32 v100, 4, v100
	v_add_u32_e32 v61, s74, v121
	v_add3_u32 v86, 0, v100, v217
	v_bitop3_b32 v100, v101, v118, 7 bitop3:0x6c
	v_lshlrev_b32_e32 v100, 4, v100
	v_add3_u32 v87, 0, v100, v217
	v_add_u32_e32 v100, 0x3fc, v61
	v_add_u32_e32 v101, 0x43c, v61
	v_cndmask_b32_e64 v92, v100, v101, s[6:7]
	v_add_u32_e32 v100, 0x400, v61
	v_add_u32_e32 v101, 0x440, v61
	v_cndmask_b32_e64 v93, v100, v101, s[10:11]
	v_add_u32_e32 v100, 0x404, v61
	v_add_u32_e32 v101, 0x444, v61
	v_cndmask_b32_e64 v94, v100, v101, s[14:15]
	v_add_u32_e32 v100, 0x408, v61
	v_add_u32_e32 v101, 0x448, v61
	v_cndmask_b32_e64 v95, v100, v101, s[18:19]
	v_lshl_add_u32 v217, v216, 7, v120
	v_bitop3_b32 v100, v216, v134, 7 bitop3:0x6c
	v_lshl_add_u32 v88, v100, 4, v217
	v_bitop3_b32 v100, v216, v135, 7 bitop3:0x6c
	v_lshl_add_u32 v89, v100, 4, v217
	v_bitop3_b32 v100, v216, v136, 7 bitop3:0x6c
	v_lshl_add_u32 v90, v100, 4, v217
	v_bitop3_b32 v100, v216, v137, 7 bitop3:0x6c
	v_lshl_add_u32 v91, v100, 4, v217
	s_lshl_b32 s26, s50, 15
	v_ashrrev_i32_e32 v61, 31, v60
	v_lshlrev_b64 v[60:61], 19, v[60:61]
	v_lshl_add_u64 v[60:61], s[40:41], 0, v[60:61]
	v_lshl_add_u64 v[60:61], v[60:61], 0, s[26:27]
	v_lshl_add_u64 v[60:61], v[60:61], 0, v[58:59]
	v_lshlrev_b32_e32 v58, 1, v104
	v_lshl_add_u64 v[60:61], v[60:61], 0, v[58:59]
	v_lshl_add_u64 v[60:61], v[60:61], 0, s[28:29]
	s_lshl_b32 s58, s55, 1
	s_lshl_b32 s59, s55, 4
	s_mov_b32 s72, s55
	ds_read_b32 v156, v92 offset:0
	ds_read_b32 v157, v93 offset:0
	ds_read_b32 v158, v94 offset:0
	ds_read_b32 v159, v95 offset:0
	v_add_u32_e32 v100, s76, v86
	v_add_u32_e32 v101, s76, v87
	ds_read_b128 v[204:207], v100
	ds_read_b128 v[208:211], v100 offset:2048
	ds_read_b128 v[212:215], v101
	ds_read_b128 v[220:223], v101 offset:2048
	s_waitcnt lgkmcnt(7)
	ds_read_b32 v160, v92 offset:128
	ds_read_b32 v161, v93 offset:128
	ds_read_b32 v162, v94 offset:128
	ds_read_b32 v163, v95 offset:128
	v_add_u32_e32 v100, s77, v86
	v_add_u32_e32 v101, s77, v87
	ds_read_b128 v[224:227], v100
	ds_read_b128 v[228:231], v100 offset:2048
	ds_read_b128 v[232:235], v101
	ds_read_b128 v[236:239], v101 offset:2048
	s_waitcnt vmcnt(6)
	s_waitcnt lgkmcnt(11)
	v_mfma_f32_16x16x32_bf16 v[188:191], v[204:207], v[82:85], v[156:159]
	s_waitcnt lgkmcnt(10)
	v_mfma_f32_16x16x32_bf16 v[192:195], v[208:211], v[82:85], v[156:159]
	s_waitcnt lgkmcnt(9)
	v_mfma_f32_16x16x32_bf16 v[188:191], v[212:215], v[78:81], v[188:191]
	s_waitcnt lgkmcnt(8)
	v_mfma_f32_16x16x32_bf16 v[192:195], v[220:223], v[78:81], v[192:195]
	s_waitcnt lgkmcnt(7)
	ds_read_b32 v164, v92 offset:256
	ds_read_b32 v165, v93 offset:256
	ds_read_b32 v166, v94 offset:256
	ds_read_b32 v167, v95 offset:256
	v_add_u32_e32 v100, s78, v86
	v_add_u32_e32 v101, s78, v87
	ds_read_b128 v[240:243], v100
	ds_read_b128 v[144:147], v100 offset:2048
	ds_read_b128 v[148:151], v101
	ds_read_b128 v[152:155], v101 offset:2048
	s_waitcnt lgkmcnt(11)
	v_mfma_f32_16x16x32_bf16 v[196:199], v[224:227], v[82:85], v[160:163]
	s_waitcnt lgkmcnt(10)
	v_mfma_f32_16x16x32_bf16 v[200:203], v[228:231], v[82:85], v[160:163]
	s_waitcnt lgkmcnt(9)
	v_mfma_f32_16x16x32_bf16 v[196:199], v[232:235], v[78:81], v[196:199]
	s_waitcnt lgkmcnt(8)
	v_mfma_f32_16x16x32_bf16 v[200:203], v[236:239], v[78:81], v[200:203]
	s_waitcnt lgkmcnt(7)
	ds_read_b32 v168, v92 offset:384
	ds_read_b32 v169, v93 offset:384
	ds_read_b32 v170, v94 offset:384
	ds_read_b32 v171, v95 offset:384
	v_add_u32_e32 v100, s79, v86
	v_add_u32_e32 v101, s79, v87
	ds_read_b128 v[204:207], v100
	ds_read_b128 v[208:211], v100 offset:2048
	ds_read_b128 v[212:215], v101
	ds_read_b128 v[220:223], v101 offset:2048
	v_cndmask_b32_e64 v156, v188, v192, s[6:7]
	v_cndmask_b32_e64 v157, v189, v193, s[10:11]
	v_cndmask_b32_e64 v158, v190, v194, s[14:15]
	v_cndmask_b32_e64 v159, v191, v195, s[18:19]
	s_waitcnt lgkmcnt(11)
	v_mfma_f32_16x16x32_bf16 v[188:191], v[240:243], v[82:85], v[164:167]
	s_waitcnt lgkmcnt(10)
	v_mfma_f32_16x16x32_bf16 v[192:195], v[144:147], v[82:85], v[164:167]
	s_waitcnt lgkmcnt(9)
	v_mfma_f32_16x16x32_bf16 v[188:191], v[148:151], v[78:81], v[188:191]
	s_waitcnt lgkmcnt(8)
	v_mfma_f32_16x16x32_bf16 v[192:195], v[152:155], v[78:81], v[192:195]
	s_waitcnt lgkmcnt(7)
; __device__ __forceinline__ void attn_b_unit(LAS unsigned char* lds, const bf16* Z, bf16* Y, int unit) {
;     ...
;         f32x4 SA0, SA1, SB0, SB1;
;         qk_at(kp0, kp1, offA, qf0, qf1, SA0, SA1);
;         qk_at(kp0, kp1, offB, qf0, qf1, SB0, SB1);
; #pragma unroll
;         for (int r = 0; r < 4; ++r) {
;             SA0[r] += tpa[r][st * 32]; SA1[r] += tpb[r][st * 32]; SB0[r] += tpa[r][st * 32 + 128]; SB1[r] += tpb[r][st * 32 + 128];
;         }
;         softmax_step(SA0, SA1, m0, l0, O0);
;         softmax_step(SB0, SB1, m1, l1, O1);
;         pv_at(vp, offA, SA0, SA1, O0);
;         pv_at(vp, offB, SB0, SB1, O1);
	ds_read_b32 v172, v92 offset:512
	ds_read_b32 v173, v93 offset:512
	ds_read_b32 v174, v94 offset:512
	ds_read_b32 v175, v95 offset:512
	v_add_u32_e32 v100, s80, v86
	v_add_u32_e32 v101, s80, v87
	ds_read_b128 v[224:227], v100
	ds_read_b128 v[228:231], v100 offset:2048
	ds_read_b128 v[232:235], v101
	ds_read_b128 v[236:239], v101 offset:2048
	v_cndmask_b32_e64 v160, v196, v200, s[6:7]
	v_cndmask_b32_e64 v161, v197, v201, s[10:11]
	v_cndmask_b32_e64 v162, v198, v202, s[14:15]
	v_cndmask_b32_e64 v163, v199, v203, s[18:19]
	s_waitcnt lgkmcnt(11)
	v_mfma_f32_16x16x32_bf16 v[196:199], v[204:207], v[82:85], v[168:171]
	s_waitcnt lgkmcnt(10)
	v_mfma_f32_16x16x32_bf16 v[200:203], v[208:211], v[82:85], v[168:171]
	s_waitcnt lgkmcnt(9)
	v_mfma_f32_16x16x32_bf16 v[196:199], v[212:215], v[78:81], v[196:199]
	s_waitcnt lgkmcnt(8)
	v_mfma_f32_16x16x32_bf16 v[200:203], v[220:223], v[78:81], v[200:203]
	s_waitcnt lgkmcnt(7)
	ds_read_b32 v176, v92 offset:640
	ds_read_b32 v177, v93 offset:640
	ds_read_b32 v178, v94 offset:640
	ds_read_b32 v179, v95 offset:640
	v_add_u32_e32 v100, s81, v86
	v_add_u32_e32 v101, s81, v87
	ds_read_b128 v[240:243], v100
	ds_read_b128 v[144:147], v100 offset:2048
	ds_read_b128 v[148:151], v101
	ds_read_b128 v[152:155], v101 offset:2048
	v_cndmask_b32_e64 v164, v188, v192, s[6:7]
	v_cndmask_b32_e64 v165, v189, v193, s[10:11]
	v_cndmask_b32_e64 v166, v190, v194, s[14:15]
	v_cndmask_b32_e64 v167, v191, v195, s[18:19]
	s_waitcnt lgkmcnt(11)
	v_mfma_f32_16x16x32_bf16 v[188:191], v[224:227], v[82:85], v[172:175]
	s_waitcnt lgkmcnt(10)
	v_mfma_f32_16x16x32_bf16 v[192:195], v[228:231], v[82:85], v[172:175]
	s_waitcnt lgkmcnt(9)
	v_mfma_f32_16x16x32_bf16 v[188:191], v[232:235], v[78:81], v[188:191]
	s_waitcnt lgkmcnt(8)
	v_mfma_f32_16x16x32_bf16 v[192:195], v[236:239], v[78:81], v[192:195]
	s_waitcnt lgkmcnt(7)
	ds_read_b32 v180, v92 offset:768
	ds_read_b32 v181, v93 offset:768
	ds_read_b32 v182, v94 offset:768
	ds_read_b32 v183, v95 offset:768
	v_add_u32_e32 v100, s82, v86
	v_add_u32_e32 v101, s82, v87
	ds_read_b128 v[204:207], v100
	ds_read_b128 v[208:211], v100 offset:2048
	ds_read_b128 v[212:215], v101
	ds_read_b128 v[220:223], v101 offset:2048
	v_cndmask_b32_e64 v168, v196, v200, s[6:7]
	v_cndmask_b32_e64 v169, v197, v201, s[10:11]
	v_cndmask_b32_e64 v170, v198, v202, s[14:15]
	v_cndmask_b32_e64 v171, v199, v203, s[18:19]
	s_waitcnt lgkmcnt(11)
	v_mfma_f32_16x16x32_bf16 v[196:199], v[240:243], v[82:85], v[176:179]
	s_waitcnt lgkmcnt(10)
	v_mfma_f32_16x16x32_bf16 v[200:203], v[144:147], v[82:85], v[176:179]
	s_waitcnt lgkmcnt(9)
	v_mfma_f32_16x16x32_bf16 v[196:199], v[148:151], v[78:81], v[196:199]
	s_waitcnt lgkmcnt(8)
	v_mfma_f32_16x16x32_bf16 v[200:203], v[152:155], v[78:81], v[200:203]
	s_waitcnt lgkmcnt(7)
	ds_read_b32 v184, v92 offset:896
	ds_read_b32 v185, v93 offset:896
	ds_read_b32 v186, v94 offset:896
	ds_read_b32 v187, v95 offset:896
	v_add_u32_e32 v100, s83, v86
	v_add_u32_e32 v101, s83, v87
	ds_read_b128 v[224:227], v100
	ds_read_b128 v[228:231], v100 offset:2048
	ds_read_b128 v[232:235], v101
	ds_read_b128 v[236:239], v101 offset:2048
	v_cndmask_b32_e64 v172, v188, v192, s[6:7]
	v_cndmask_b32_e64 v173, v189, v193, s[10:11]
	v_cndmask_b32_e64 v174, v190, v194, s[14:15]
	v_cndmask_b32_e64 v175, v191, v195, s[18:19]
	s_waitcnt lgkmcnt(11)
	v_mfma_f32_16x16x32_bf16 v[188:191], v[204:207], v[82:85], v[180:183]
	s_waitcnt lgkmcnt(10)
	v_mfma_f32_16x16x32_bf16 v[192:195], v[208:211], v[82:85], v[180:183]
	s_waitcnt lgkmcnt(9)
	v_mfma_f32_16x16x32_bf16 v[188:191], v[212:215], v[78:81], v[188:191]
	s_waitcnt lgkmcnt(8)
	v_mfma_f32_16x16x32_bf16 v[192:195], v[220:223], v[78:81], v[192:195]
	v_cndmask_b32_e64 v176, v196, v200, s[6:7]
	v_cndmask_b32_e64 v177, v197, v201, s[10:11]
	v_cndmask_b32_e64 v178, v198, v202, s[14:15]
	v_cndmask_b32_e64 v179, v199, v203, s[18:19]
	s_waitcnt lgkmcnt(3)
	v_mfma_f32_16x16x32_bf16 v[196:199], v[224:227], v[82:85], v[184:187]
	s_waitcnt lgkmcnt(2)
	v_mfma_f32_16x16x32_bf16 v[200:203], v[228:231], v[82:85], v[184:187]
	s_waitcnt lgkmcnt(1)
	v_mfma_f32_16x16x32_bf16 v[196:199], v[232:235], v[78:81], v[196:199]
	s_waitcnt lgkmcnt(0)
	v_mfma_f32_16x16x32_bf16 v[200:203], v[236:239], v[78:81], v[200:203]
	v_cndmask_b32_e64 v180, v188, v192, s[6:7]
	v_cndmask_b32_e64 v181, v189, v193, s[10:11]
	v_cndmask_b32_e64 v182, v190, v194, s[14:15]
	v_cndmask_b32_e64 v183, v191, v195, s[18:19]
	v_add_u32_e32 v219, s76, v88
	v_add_u32_e32 v86, s76, v89
	v_add_u32_e32 v87, s76, v90
	v_add_u32_e32 v92, s76, v91
	ds_read_b64_tr_b16 v[212:213], v219
	ds_read_b64_tr_b16 v[214:215], v219 offset:2048
	ds_read_b64_tr_b16 v[220:221], v86
	ds_read_b64_tr_b16 v[222:223], v86 offset:2048
	ds_read_b64_tr_b16 v[224:225], v87
	ds_read_b64_tr_b16 v[226:227], v87 offset:2048
	ds_read_b64_tr_b16 v[228:229], v92
	ds_read_b64_tr_b16 v[230:231], v92 offset:2048
	v_mov_b32_e32 v100, 0xffff
	v_mov_b32_e32 v101, 0xffff0000
	v_cndmask_b32_e64 v96, v100, 0, s[6:7]
	v_cndmask_b32_e64 v216, v101, 0, s[10:11]
	v_cndmask_b32_e64 v97, v100, 0, s[14:15]
	v_cndmask_b32_e64 v217, v101, 0, s[18:19]
	v_cndmask_b32_e64 v184, v196, v200, s[6:7]
	v_cndmask_b32_e64 v185, v197, v201, s[10:11]
	v_cndmask_b32_e64 v186, v198, v202, s[14:15]
	v_cndmask_b32_e64 v187, v199, v203, s[18:19]
	v_or_b32_e32 v96, v96, v216
	v_or_b32_e32 v97, v97, v217
	v_not_b32_e32 v98, v96
	v_not_b32_e32 v99, v97
	s_waitcnt lgkmcnt(7)
; #define LAS __attribute__((address_space(3)))
; __device__ __forceinline__ unsigned pk2(float lo, float hi) { return pg8::cvt_pk_bf16(lo, hi); }
; __device__ __forceinline__ s16x4 vtr(const LAS unsigned char* p) { return __builtin_bit_cast(s16x4, __builtin_amdgcn_ds_read_tr16_b64_v4i16((LAS s16x4*)p)); }
; #define MFMA16(a, b, c) __builtin_amdgcn_mfma_f32_16x16x32_bf16((a), (b), (c), 0, 0, 0)
; __device__ __forceinline__ void pv_at(const LAS unsigned char* const (&vp)[4], int off, const f32x4& P0, const f32x4& P1, f32x4 (&O)[4]) {
;     v4u pw; pw.x = pk2(P0[0], P0[1]); pw.y = pk2(P0[2], P0[3]); pw.z = pk2(P1[0], P1[1]); pw.w = pk2(P1[2], P1[3]);
;     const bf16x8 pb = __builtin_bit_cast(bf16x8, pw);
; #pragma unroll
;     for (int db = 0; db < 4; ++db) {
;         const s16x4 lo = vtr(vp[db] + off), hi = vtr(vp[db] + off + 2048);
;         const bf16x8 vt = (bf16x8){lo[0], lo[1], lo[2], lo[3], hi[0], hi[1], hi[2], hi[3]};
;         O[db] = MFMA16(vt, pb, O[db]);
;     }
; }
; __device__ __forceinline__ void softmax_step(f32x4& s0, f32x4& s1, float& m, float& l, f32x4 (&O)[4]) {
;     float t = fmaxf(fmaxf(fmaxf(s0[0], s0[1]), fmaxf(s0[2], s0[3])), fmaxf(fmaxf(s1[0], s1[1]), fmaxf(s1[2], s1[3])));
;     t = xrow16_max(t);
;     const float mn = fmaxf(m, t), alpha = __builtin_amdgcn_exp2f(m - mn);
;     m = mn;
; #pragma unroll
;     for (int k = 0; k < 4; ++k) { s0[k] = __builtin_amdgcn_exp2f(s0[k] - mn); s1[k] = __builtin_amdgcn_exp2f(s1[k] - mn); }
;     l = l * alpha + ((s0[0] + s0[1]) + (s0[2] + s0[3])) + ((s1[0] + s1[1]) + (s1[2] + s1[3]));
; #pragma unroll
;     for (int db = 0; db < 4; ++db) O[db] *= alpha;
; }
	v_add_u32_e32 v219, s77, v88
	v_add_u32_e32 v86, s77, v89
	v_add_u32_e32 v87, s77, v90
	v_add_u32_e32 v92, s77, v91
	ds_read_b64_tr_b16 v[232:233], v219
	ds_read_b64_tr_b16 v[234:235], v219 offset:2048
	ds_read_b64_tr_b16 v[236:237], v86
	ds_read_b64_tr_b16 v[238:239], v86 offset:2048
	ds_read_b64_tr_b16 v[240:241], v87
	ds_read_b64_tr_b16 v[242:243], v87 offset:2048
	ds_read_b64_tr_b16 v[144:145], v92
	ds_read_b64_tr_b16 v[146:147], v92 offset:2048
	v_max3_f32 v142, v156, v157, v158
	v_max3_f32 v143, v164, v165, v166
	v_max3_f32 v216, v172, v173, v174
	v_max3_f32 v217, v180, v181, v182
	v_max3_f32 v142, v142, v159, v160
	v_max3_f32 v143, v143, v167, v168
	v_max3_f32 v216, v216, v175, v176
	v_max3_f32 v217, v217, v183, v184
	v_max3_f32 v142, v142, v161, v162
	v_max3_f32 v143, v143, v169, v170
	v_max3_f32 v216, v216, v177, v178
	v_max3_f32 v217, v217, v185, v186
	v_max_f32_e32 v142, v142, v163
	v_max_f32_e32 v143, v143, v171
	v_max_f32_e32 v216, v216, v179
	v_max_f32_e32 v217, v217, v187
	v_max3_f32 v244, v142, v143, v216
	v_max_f32_e32 v244, v244, v217
	v_mov_b32_e32 v100, v244
	s_nop 1
	v_permlane16_swap_b32_e32 v244, v100
	v_max_f32_e32 v244, v244, v100
	v_mov_b32_e32 v100, v244
	s_nop 1
	v_permlane32_swap_b32_e32 v244, v100
	v_max3_f32 v244, v244, v100, s54
	v_pk_add_f32 v[156:157], v[156:157], v[244:245] op_sel_hi:[1,0] neg_lo:[0,1] neg_hi:[0,1]
	v_pk_add_f32 v[158:159], v[158:159], v[244:245] op_sel_hi:[1,0] neg_lo:[0,1] neg_hi:[0,1]
	v_pk_add_f32 v[160:161], v[160:161], v[244:245] op_sel_hi:[1,0] neg_lo:[0,1] neg_hi:[0,1]
	v_pk_add_f32 v[162:163], v[162:163], v[244:245] op_sel_hi:[1,0] neg_lo:[0,1] neg_hi:[0,1]
	v_pk_add_f32 v[164:165], v[164:165], v[244:245] op_sel_hi:[1,0] neg_lo:[0,1] neg_hi:[0,1]
	v_pk_add_f32 v[166:167], v[166:167], v[244:245] op_sel_hi:[1,0] neg_lo:[0,1] neg_hi:[0,1]
	v_pk_add_f32 v[168:169], v[168:169], v[244:245] op_sel_hi:[1,0] neg_lo:[0,1] neg_hi:[0,1]
	v_pk_add_f32 v[170:171], v[170:171], v[244:245] op_sel_hi:[1,0] neg_lo:[0,1] neg_hi:[0,1]
	v_pk_add_f32 v[172:173], v[172:173], v[244:245] op_sel_hi:[1,0] neg_lo:[0,1] neg_hi:[0,1]
	v_pk_add_f32 v[174:175], v[174:175], v[244:245] op_sel_hi:[1,0] neg_lo:[0,1] neg_hi:[0,1]
	v_pk_add_f32 v[176:177], v[176:177], v[244:245] op_sel_hi:[1,0] neg_lo:[0,1] neg_hi:[0,1]
	v_pk_add_f32 v[178:179], v[178:179], v[244:245] op_sel_hi:[1,0] neg_lo:[0,1] neg_hi:[0,1]
	v_pk_add_f32 v[180:181], v[180:181], v[244:245] op_sel_hi:[1,0] neg_lo:[0,1] neg_hi:[0,1]
	v_pk_add_f32 v[182:183], v[182:183], v[244:245] op_sel_hi:[1,0] neg_lo:[0,1] neg_hi:[0,1]
	v_pk_add_f32 v[184:185], v[184:185], v[244:245] op_sel_hi:[1,0] neg_lo:[0,1] neg_hi:[0,1]
	v_pk_add_f32 v[186:187], v[186:187], v[244:245] op_sel_hi:[1,0] neg_lo:[0,1] neg_hi:[0,1]
	v_exp_f32_e32 v156, v156
	v_exp_f32_e32 v157, v157
	v_exp_f32_e32 v158, v158
	v_exp_f32_e32 v159, v159
	v_exp_f32_e32 v160, v160
	v_exp_f32_e32 v161, v161
	v_exp_f32_e32 v162, v162
	v_exp_f32_e32 v163, v163
	v_exp_f32_e32 v164, v164
	v_exp_f32_e32 v165, v165
	v_exp_f32_e32 v166, v166
	v_exp_f32_e32 v167, v167
	v_exp_f32_e32 v168, v168
	v_exp_f32_e32 v169, v169
	v_exp_f32_e32 v170, v170
	v_exp_f32_e32 v171, v171
	v_exp_f32_e32 v172, v172
	v_exp_f32_e32 v173, v173
	v_exp_f32_e32 v174, v174
	v_exp_f32_e32 v175, v175
	v_exp_f32_e32 v176, v176
	v_exp_f32_e32 v177, v177
	v_exp_f32_e32 v178, v178
	v_exp_f32_e32 v179, v179
	v_exp_f32_e32 v180, v180
	v_exp_f32_e32 v181, v181
	v_exp_f32_e32 v182, v182
	v_exp_f32_e32 v183, v183
	v_exp_f32_e32 v184, v184
	v_exp_f32_e32 v185, v185
	v_exp_f32_e32 v186, v186
	v_exp_f32_e32 v187, v187
	v_pk_add_f32 v[148:149], v[156:157], v[158:159]
	v_pk_add_f32 v[150:151], v[164:165], v[166:167]
	v_pk_add_f32 v[152:153], v[172:173], v[174:175]
	v_pk_add_f32 v[154:155], v[180:181], v[182:183]
	v_pk_add_f32 v[148:149], v[148:149], v[160:161]
	v_pk_add_f32 v[150:151], v[150:151], v[168:169]
	v_pk_add_f32 v[152:153], v[152:153], v[176:177]
	v_pk_add_f32 v[154:155], v[154:155], v[184:185]
	v_pk_add_f32 v[148:149], v[148:149], v[162:163]
	v_pk_add_f32 v[150:151], v[150:151], v[170:171]
	v_pk_add_f32 v[152:153], v[152:153], v[178:179]
	v_pk_add_f32 v[154:155], v[154:155], v[186:187]
	v_pk_add_f32 v[148:149], v[148:149], v[150:151]
	v_pk_add_f32 v[152:153], v[152:153], v[154:155]
	v_pk_add_f32 v[148:149], v[148:149], v[152:153]
	v_add_f32_e32 v245, v148, v149
	v_cvt_pk_bf16_f32 v100, v156, v157
	v_cvt_pk_bf16_f32 v101, v158, v159
	v_and_b32_e32 v188, v100, v96
	v_and_b32_e32 v189, v101, v97
	v_and_b32_e32 v190, v100, v98
	v_and_b32_e32 v191, v101, v99
	s_nop 1
	s_waitcnt lgkmcnt(14)
	v_mfma_f32_16x16x32_bf16 v[196:199], v[212:215], v[188:191], 0
	s_waitcnt lgkmcnt(12)
	v_mfma_f32_16x16x32_bf16 v[200:203], v[220:223], v[188:191], 0
	s_waitcnt lgkmcnt(10)
	v_mfma_f32_16x16x32_bf16 v[204:207], v[224:227], v[188:191], 0
	s_waitcnt lgkmcnt(8)
	v_mfma_f32_16x16x32_bf16 v[208:211], v[228:231], v[188:191], 0
	v_cvt_pk_bf16_f32 v100, v160, v161
	v_cvt_pk_bf16_f32 v101, v162, v163
	v_and_b32_e32 v192, v100, v96
	v_and_b32_e32 v193, v101, v97
	v_and_b32_e32 v194, v100, v98
	v_and_b32_e32 v195, v101, v99
	s_waitcnt lgkmcnt(7)
	v_add_u32_e32 v219, s78, v88
	v_add_u32_e32 v86, s78, v89
	v_add_u32_e32 v87, s78, v90
	v_add_u32_e32 v92, s78, v91
	ds_read_b64_tr_b16 v[212:213], v219
	ds_read_b64_tr_b16 v[214:215], v219 offset:2048
	ds_read_b64_tr_b16 v[220:221], v86
	ds_read_b64_tr_b16 v[222:223], v86 offset:2048
	ds_read_b64_tr_b16 v[224:225], v87
	ds_read_b64_tr_b16 v[226:227], v87 offset:2048
	ds_read_b64_tr_b16 v[228:229], v92
	ds_read_b64_tr_b16 v[230:231], v92 offset:2048
	s_waitcnt lgkmcnt(14)
	v_mfma_f32_16x16x32_bf16 v[196:199], v[232:235], v[192:195], v[196:199]
	s_waitcnt lgkmcnt(12)
; #define LAS __attribute__((address_space(3)))
; __device__ __forceinline__ unsigned pk2(float lo, float hi) { return pg8::cvt_pk_bf16(lo, hi); }
; __device__ __forceinline__ s16x4 vtr(const LAS unsigned char* p) { return __builtin_bit_cast(s16x4, __builtin_amdgcn_ds_read_tr16_b64_v4i16((LAS s16x4*)p)); }
; #define MFMA16(a, b, c) __builtin_amdgcn_mfma_f32_16x16x32_bf16((a), (b), (c), 0, 0, 0)
; __device__ __forceinline__ void pv_at(const LAS unsigned char* const (&vp)[4], int off, const f32x4& P0, const f32x4& P1, f32x4 (&O)[4]) {
;     v4u pw; pw.x = pk2(P0[0], P0[1]); pw.y = pk2(P0[2], P0[3]); pw.z = pk2(P1[0], P1[1]); pw.w = pk2(P1[2], P1[3]);
;     const bf16x8 pb = __builtin_bit_cast(bf16x8, pw);
; #pragma unroll
;     for (int db = 0; db < 4; ++db) {
;         const s16x4 lo = vtr(vp[db] + off), hi = vtr(vp[db] + off + 2048);
;         const bf16x8 vt = (bf16x8){lo[0], lo[1], lo[2], lo[3], hi[0], hi[1], hi[2], hi[3]};
;         O[db] = MFMA16(vt, pb, O[db]);
;     }
; }
	v_mfma_f32_16x16x32_bf16 v[200:203], v[236:239], v[192:195], v[200:203]
	s_waitcnt lgkmcnt(10)
	v_mfma_f32_16x16x32_bf16 v[204:207], v[240:243], v[192:195], v[204:207]
	s_waitcnt lgkmcnt(8)
	v_mfma_f32_16x16x32_bf16 v[208:211], v[144:147], v[192:195], v[208:211]
	v_cvt_pk_bf16_f32 v100, v164, v165
	v_cvt_pk_bf16_f32 v101, v166, v167
	v_and_b32_e32 v188, v100, v96
	v_and_b32_e32 v189, v101, v97
	v_and_b32_e32 v190, v100, v98
	v_and_b32_e32 v191, v101, v99
	s_waitcnt lgkmcnt(7)
	v_add_u32_e32 v219, s79, v88
	v_add_u32_e32 v86, s79, v89
	v_add_u32_e32 v87, s79, v90
	v_add_u32_e32 v92, s79, v91
	ds_read_b64_tr_b16 v[232:233], v219
	ds_read_b64_tr_b16 v[234:235], v219 offset:2048
	ds_read_b64_tr_b16 v[236:237], v86
	ds_read_b64_tr_b16 v[238:239], v86 offset:2048
	ds_read_b64_tr_b16 v[240:241], v87
	ds_read_b64_tr_b16 v[242:243], v87 offset:2048
	ds_read_b64_tr_b16 v[144:145], v92
	ds_read_b64_tr_b16 v[146:147], v92 offset:2048
	s_waitcnt lgkmcnt(14)
	v_mfma_f32_16x16x32_bf16 v[196:199], v[212:215], v[188:191], v[196:199]
	s_waitcnt lgkmcnt(12)
	v_mfma_f32_16x16x32_bf16 v[200:203], v[220:223], v[188:191], v[200:203]
	s_waitcnt lgkmcnt(10)
	v_mfma_f32_16x16x32_bf16 v[204:207], v[224:227], v[188:191], v[204:207]
	s_waitcnt lgkmcnt(8)
	v_mfma_f32_16x16x32_bf16 v[208:211], v[228:231], v[188:191], v[208:211]
	v_cvt_pk_bf16_f32 v100, v168, v169
	v_cvt_pk_bf16_f32 v101, v170, v171
	v_and_b32_e32 v192, v100, v96
	v_and_b32_e32 v193, v101, v97
	v_and_b32_e32 v194, v100, v98
	v_and_b32_e32 v195, v101, v99
	s_waitcnt lgkmcnt(7)
	v_add_u32_e32 v219, s80, v88
	v_add_u32_e32 v86, s80, v89
	v_add_u32_e32 v87, s80, v90
	v_add_u32_e32 v92, s80, v91
	ds_read_b64_tr_b16 v[212:213], v219
	ds_read_b64_tr_b16 v[214:215], v219 offset:2048
	ds_read_b64_tr_b16 v[220:221], v86
	ds_read_b64_tr_b16 v[222:223], v86 offset:2048
	ds_read_b64_tr_b16 v[224:225], v87
	ds_read_b64_tr_b16 v[226:227], v87 offset:2048
	ds_read_b64_tr_b16 v[228:229], v92
	ds_read_b64_tr_b16 v[230:231], v92 offset:2048
	s_waitcnt lgkmcnt(14)
	v_mfma_f32_16x16x32_bf16 v[196:199], v[232:235], v[192:195], v[196:199]
	s_waitcnt lgkmcnt(12)
	v_mfma_f32_16x16x32_bf16 v[200:203], v[236:239], v[192:195], v[200:203]
	s_waitcnt lgkmcnt(10)
	v_mfma_f32_16x16x32_bf16 v[204:207], v[240:243], v[192:195], v[204:207]
	s_waitcnt lgkmcnt(8)
	v_mfma_f32_16x16x32_bf16 v[208:211], v[144:147], v[192:195], v[208:211]
	v_cvt_pk_bf16_f32 v100, v172, v173
	v_cvt_pk_bf16_f32 v101, v174, v175
	v_and_b32_e32 v188, v100, v96
	v_and_b32_e32 v189, v101, v97
	v_and_b32_e32 v190, v100, v98
	v_and_b32_e32 v191, v101, v99
	s_waitcnt lgkmcnt(7)
	v_add_u32_e32 v219, s81, v88
	v_add_u32_e32 v86, s81, v89
	v_add_u32_e32 v87, s81, v90
	v_add_u32_e32 v92, s81, v91
	ds_read_b64_tr_b16 v[232:233], v219
	ds_read_b64_tr_b16 v[234:235], v219 offset:2048
	ds_read_b64_tr_b16 v[236:237], v86
	ds_read_b64_tr_b16 v[238:239], v86 offset:2048
	ds_read_b64_tr_b16 v[240:241], v87
	ds_read_b64_tr_b16 v[242:243], v87 offset:2048
	ds_read_b64_tr_b16 v[144:145], v92
	ds_read_b64_tr_b16 v[146:147], v92 offset:2048
	s_waitcnt lgkmcnt(14)
	v_mfma_f32_16x16x32_bf16 v[196:199], v[212:215], v[188:191], v[196:199]
	s_waitcnt lgkmcnt(12)
	v_mfma_f32_16x16x32_bf16 v[200:203], v[220:223], v[188:191], v[200:203]
	s_waitcnt lgkmcnt(10)
	v_mfma_f32_16x16x32_bf16 v[204:207], v[224:227], v[188:191], v[204:207]
	s_waitcnt lgkmcnt(8)
	v_mfma_f32_16x16x32_bf16 v[208:211], v[228:231], v[188:191], v[208:211]
	v_cvt_pk_bf16_f32 v100, v176, v177
	v_cvt_pk_bf16_f32 v101, v178, v179
	v_and_b32_e32 v192, v100, v96
	v_and_b32_e32 v193, v101, v97
	v_and_b32_e32 v194, v100, v98
	v_and_b32_e32 v195, v101, v99
	s_waitcnt lgkmcnt(7)
	v_add_u32_e32 v219, s82, v88
	v_add_u32_e32 v86, s82, v89
	v_add_u32_e32 v87, s82, v90
	v_add_u32_e32 v92, s82, v91
	ds_read_b64_tr_b16 v[212:213], v219
	ds_read_b64_tr_b16 v[214:215], v219 offset:2048
	ds_read_b64_tr_b16 v[220:221], v86
	ds_read_b64_tr_b16 v[222:223], v86 offset:2048
	ds_read_b64_tr_b16 v[224:225], v87
	ds_read_b64_tr_b16 v[226:227], v87 offset:2048
	ds_read_b64_tr_b16 v[228:229], v92
	ds_read_b64_tr_b16 v[230:231], v92 offset:2048
	s_waitcnt lgkmcnt(14)
; __device__ __forceinline__ unsigned pk2(float lo, float hi) { return pg8::cvt_pk_bf16(lo, hi); }
; __device__ __forceinline__ void store_o(bf16* yrow, int g, float l, const f32x4 (&O)[4]) {
;     const float inv = 1.0f / xrow16_sum(l);
;     unsigned wx[4], wy[4];
; #pragma unroll
;     for (int db = 0; db < 4; ++db) { wx[db] = pk2(O[db][0] * inv, O[db][1] * inv); wy[db] = pk2(O[db][2] * inv, O[db][3] * inv); }
; #pragma unroll
;     for (int p = 0; p < 2; ++p) {
;         auto rx = __builtin_amdgcn_permlane16_swap(wx[2 * p], wx[2 * p + 1], false, false); wx[2 * p] = rx[0]; wx[2 * p + 1] = rx[1];
;         auto ry = __builtin_amdgcn_permlane16_swap(wy[2 * p], wy[2 * p + 1], false, false); wy[2 * p] = ry[0]; wy[2 * p + 1] = ry[1]; }
; #pragma unroll
;     for (int p = 0; p < 2; ++p) {
;         auto rx = __builtin_amdgcn_permlane32_swap(wx[p], wx[p + 2], false, false); wx[p] = rx[0]; wx[p + 2] = rx[1];
;         auto ry = __builtin_amdgcn_permlane32_swap(wy[p], wy[p + 2], false, false); wy[p] = ry[0]; wy[p + 2] = ry[1]; }
;     v4u lo = {wx[0], wy[0], wx[1], wy[1]}, hi = {wx[2], wy[2], wx[3], wy[3]};
;     *(v4u*)(yrow + 16 * g) = lo; *(v4u*)(yrow + 16 * g + 8) = hi;
; }
	v_mfma_f32_16x16x32_bf16 v[196:199], v[232:235], v[192:195], v[196:199]
	s_waitcnt lgkmcnt(12)
	v_mfma_f32_16x16x32_bf16 v[200:203], v[236:239], v[192:195], v[200:203]
	s_waitcnt lgkmcnt(10)
	v_mfma_f32_16x16x32_bf16 v[204:207], v[240:243], v[192:195], v[204:207]
	s_waitcnt lgkmcnt(8)
	v_mfma_f32_16x16x32_bf16 v[208:211], v[144:147], v[192:195], v[208:211]
	v_cvt_pk_bf16_f32 v100, v180, v181
	v_cvt_pk_bf16_f32 v101, v182, v183
	v_and_b32_e32 v188, v100, v96
	v_and_b32_e32 v189, v101, v97
	v_and_b32_e32 v190, v100, v98
	v_and_b32_e32 v191, v101, v99
	s_waitcnt lgkmcnt(7)
	v_add_u32_e32 v219, s83, v88
	v_add_u32_e32 v86, s83, v89
	v_add_u32_e32 v87, s83, v90
	v_add_u32_e32 v92, s83, v91
	ds_read_b64_tr_b16 v[232:233], v219
	ds_read_b64_tr_b16 v[234:235], v219 offset:2048
	ds_read_b64_tr_b16 v[236:237], v86
	ds_read_b64_tr_b16 v[238:239], v86 offset:2048
	ds_read_b64_tr_b16 v[240:241], v87
	ds_read_b64_tr_b16 v[242:243], v87 offset:2048
	ds_read_b64_tr_b16 v[144:145], v92
	ds_read_b64_tr_b16 v[146:147], v92 offset:2048
	s_waitcnt lgkmcnt(14)
	v_mfma_f32_16x16x32_bf16 v[196:199], v[212:215], v[188:191], v[196:199]
	s_waitcnt lgkmcnt(12)
	v_mfma_f32_16x16x32_bf16 v[200:203], v[220:223], v[188:191], v[200:203]
	s_waitcnt lgkmcnt(10)
	v_mfma_f32_16x16x32_bf16 v[204:207], v[224:227], v[188:191], v[204:207]
	s_waitcnt lgkmcnt(8)
	v_mfma_f32_16x16x32_bf16 v[208:211], v[228:231], v[188:191], v[208:211]
	v_cvt_pk_bf16_f32 v100, v184, v185
	v_cvt_pk_bf16_f32 v101, v186, v187
	v_and_b32_e32 v192, v100, v96
	v_and_b32_e32 v193, v101, v97
	v_and_b32_e32 v194, v100, v98
	v_and_b32_e32 v195, v101, v99
	s_nop 1
	s_waitcnt lgkmcnt(6)
	v_mfma_f32_16x16x32_bf16 v[196:199], v[232:235], v[192:195], v[196:199]
	s_waitcnt lgkmcnt(4)
	v_mfma_f32_16x16x32_bf16 v[200:203], v[236:239], v[192:195], v[200:203]
	s_waitcnt lgkmcnt(2)
	v_mfma_f32_16x16x32_bf16 v[204:207], v[240:243], v[192:195], v[204:207]
	s_waitcnt lgkmcnt(0)
	v_mfma_f32_16x16x32_bf16 v[208:211], v[144:147], v[192:195], v[208:211]
	v_mov_b32_e32 v100, v245
	s_nop 1
	v_permlane16_swap_b32_e32 v245, v100
	v_add_f32_e32 v245, v245, v100
	v_mov_b32_e32 v100, v245
	s_nop 1
	v_permlane32_swap_b32_e32 v245, v100
	v_add_f32_e32 v245, v245, v100
	v_div_scale_f32 v142, s[50:51], v245, v245, 1.0
	v_div_scale_f32 v216, vcc, 1.0, v245, 1.0
	v_rcp_f32_e32 v143, v142
	s_nop 0
	v_fma_f32 v217, -v142, v143, 1.0
	v_fmac_f32_e32 v143, v217, v143
	v_mul_f32_e32 v148, v216, v143
	v_fma_f32 v149, -v142, v148, v216
	v_fmac_f32_e32 v148, v149, v143
	v_fma_f32 v216, -v142, v148, v216
	v_div_fmas_f32 v216, v216, v143, v148
	v_div_fixup_f32 v216, v216, v245, 1.0
	v_mul_f32_e32 v100, v196, v216
	v_mul_f32_e32 v101, v197, v216
	v_mul_f32_e32 v142, v198, v216
	v_mul_f32_e32 v143, v199, v216
	v_cvt_pk_bf16_f32 v78, v100, v101
	v_cvt_pk_bf16_f32 v79, v142, v143
	v_mul_f32_e32 v100, v200, v216
	v_mul_f32_e32 v101, v201, v216
	v_mul_f32_e32 v142, v202, v216
	v_mul_f32_e32 v143, v203, v216
	v_cvt_pk_bf16_f32 v80, v100, v101
	v_cvt_pk_bf16_f32 v81, v142, v143
	v_mul_f32_e32 v100, v204, v216
	v_mul_f32_e32 v101, v205, v216
	v_mul_f32_e32 v142, v206, v216
	v_mul_f32_e32 v143, v207, v216
	v_cvt_pk_bf16_f32 v82, v100, v101
	v_cvt_pk_bf16_f32 v83, v142, v143
	v_mul_f32_e32 v100, v208, v216
	v_mul_f32_e32 v101, v209, v216
	v_mul_f32_e32 v142, v210, v216
	v_mul_f32_e32 v143, v211, v216
	v_cvt_pk_bf16_f32 v84, v100, v101
	v_cvt_pk_bf16_f32 v85, v142, v143
	s_nop 1
	v_permlane16_swap_b32_e32 v78, v80
	v_permlane16_swap_b32_e32 v79, v81
	v_permlane16_swap_b32_e32 v82, v84
	v_permlane16_swap_b32_e32 v83, v85
	s_nop 0
	v_permlane32_swap_b32_e32 v78, v82
	v_permlane32_swap_b32_e32 v79, v83
	v_permlane32_swap_b32_e32 v80, v84
	v_permlane32_swap_b32_e32 v81, v85
	s_andn2_b64 vcc, exec, s[44:45]
	global_store_dwordx4 v[60:61], v[78:81], off
	global_store_dwordx4 v[60:61], v[82:85], off offset:16
	s_barrier
	s_cbranch_vccz .LBB0_294

; __device__ __forceinline__ size_t tmo(int row, int ct, int nct) { return ((size_t)(row >> 8) * nct + ct) * 32768 + (size_t)(row & 255) * 128; }
; __device__ __forceinline__ void attn_b_unit(LAS unsigned char* lds, const bf16* Z, bf16* Y, int unit) {
;     ...
;     const size_t qtok = tok0 + (size_t)rq * 64 + c;
;     const unsigned char* qp = (const unsigned char*)Z + tmo((int)qtok, Z_QB / 64 + h, ZLD / 64) + 16 * g;
;     const bf16x8 qf0 = *(const bf16x8*)qp, qf1 = *(const bf16x8*)(qp + 64);
; __global__ void __launch_bounds__(NTHREADS, 2) mk_fwd(Args args) {
;     ...
;             v4u kr[9], vr[9]; float tr[2]; int u = vcu; const int NU = BATCH * 8 * 64;
;             if (u < NU) attn_b_prefetch(Zb, rpb, u, kr, vr, tr);
;             for (; u < NU; u += G) {
;                 attn_b_commit(lds, kr, vr, tr);
;                 __syncthreads();
;                 if (u + G < NU) attn_b_prefetch(Zb, rpb, u + G, kr, vr, tr);
;                 asm volatile("" ::: "memory");
;                 attn_b_unit(lds, Zb, YA, u);
;                 __syncthreads();
;             }
.Lb_commit_done:
	s_add_i32 s55, s72, s90
	s_and_b32 s50, s55, 15
	s_min_u32 s50, s50, 1
	s_cmpk_lt_i32 s55, 0x1000
	s_cselect_b32 s51, 1, 0
	s_cmp_lg_u32 s91, 0
	s_cselect_b32 s26, s50, s51
	s_cmp_lg_u32 s26, 0
	s_cselect_b64 s[44:45], 0, -1
	s_mov_b32 s97, s26
	s_cmp_lg_u32 s91, 0
	s_cbranch_scc0 .Lb_q_direct
	s_cmp_lg_u32 s32, 0
	s_cbranch_scc0 .Lb_q_direct
	s_waitcnt vmcnt(0)
	v_mov_b32_e32 v82, v20
	v_mov_b32_e32 v83, v21
	v_mov_b32_e32 v84, v22
	v_mov_b32_e32 v85, v23
	v_mov_b32_e32 v78, v24
	v_mov_b32_e32 v79, v25
	v_mov_b32_e32 v80, v26
	v_mov_b32_e32 v81, v27
	s_branch .Lb_q_next
.Lb_q_direct:
	s_and_b32 s51, s58, 0x7e
	v_add_u32_e32 v86, s51, v115
	s_and_b32 s26, s59, 0xffffe000
	v_lshlrev_b32_e32 v87, 6, v86
	v_add_u32_e32 v88, s26, v87
	s_bfe_u32 s50, s72, 0x30006
	v_ashrrev_i32_e32 v88, 8, v88
	s_add_i32 s26, s50, 12
	v_mul_hi_i32_i24_e32 v91, 0x44, v88
	v_mul_i32_i24_e32 v90, 0x44, v88
	v_or_b32_e32 v87, v87, v116
	v_lshl_add_u64 v[90:91], v[90:91], 0, s[26:27]
	v_lshlrev_b64 v[90:91], 15, v[90:91]
	v_lshlrev_b32_e32 v87, 7, v87
	v_and_b32_e32 v88, 0x7f80, v87
	v_mov_b32_e32 v89, 0
	v_lshl_add_u64 v[90:91], s[38:39], 0, v[90:91]
	v_lshl_add_u64 v[90:91], v[90:91], 0, v[88:89]
	v_lshl_add_u64 v[90:91], v[90:91], 0, v[104:105]
	global_load_dwordx4 v[82:85], v[90:91], off
	global_load_dwordx4 v[78:81], v[90:91], off offset:64
	s_cmp_lg_u32 s91, 0
	s_cbranch_scc0 .Lb_q_done
	s_waitcnt vmcnt(0)
.Lb_q_next:
	s_mov_b32 s32, 0
	s_cmp_eq_u32 s97, 0
	s_cbranch_scc1 .Lb_q_done
	s_lshl_b32 s56, s55, 1
	s_lshl_b32 s57, s55, 4
	s_and_b32 s51, s56, 0x7e
	v_add_u32_e32 v86, s51, v115
	s_and_b32 s26, s57, 0xffffe000
	v_lshlrev_b32_e32 v87, 6, v86
	v_add_u32_e32 v88, s26, v87
	s_bfe_u32 s50, s55, 0x30006
	v_ashrrev_i32_e32 v88, 8, v88
	s_add_i32 s26, s50, 12
	v_mul_hi_i32_i24_e32 v91, 0x44, v88
	v_mul_i32_i24_e32 v90, 0x44, v88
	v_or_b32_e32 v87, v87, v116
	v_lshl_add_u64 v[90:91], v[90:91], 0, s[26:27]
	v_lshlrev_b64 v[90:91], 15, v[90:91]
	v_lshlrev_b32_e32 v87, 7, v87
	v_and_b32_e32 v88, 0x7f80, v87
	v_mov_b32_e32 v89, 0
	v_lshl_add_u64 v[90:91], s[38:39], 0, v[90:91]
	v_lshl_add_u64 v[90:91], v[90:91], 0, v[88:89]
	v_lshl_add_u64 v[90:91], v[90:91], 0, v[104:105]
	global_load_dwordx4 v[20:23], v[90:91], off
	global_load_dwordx4 v[24:27], v[90:91], off offset:64
	s_mov_b32 s32, 1
.Lb_q_done:
	s_mov_b32 s26, s97
	s_waitcnt lgkmcnt(0)
	s_barrier
	s_cmp_eq_u32 s26, 0
	s_cbranch_scc1 .Lb_nonext
	s_cmp_lg_u32 s91, 0
	s_cbranch_scc1 .Lb_small_prefetch
	s_add_i32 s57, s3, s58
	s_and_b32 s26, s57, 0x7e
	v_sub_co_u32_e64 v2, s[50:51], s26, 4
	s_add_i32 s56, s1, s59
	v_readfirstlane_b32 s26, v2
	s_bfe_u32 s73, s55, 0x30006
	s_and_b32 s74, s56, 0xffffe000
	s_min_u32 s26, s26, 0x78
	s_and_b64 s[50:51], s[50:51], exec
	s_cselect_b32 s75, 0, s26
	v_or_b32_e32 v60, s75, v106
	v_lshlrev_b32_e32 v70, 6, v60
	v_or_b32_e32 v2, s74, v70
	v_add_u32_e32 v10, 64, v70
	v_lshrrev_b32_e32 v2, 8, v2
	v_or_b32_e32 v11, s74, v10
	v_add_u32_e32 v18, 0x80, v70
	v_mul_i32_i24_e32 v2, 0x44, v2
	v_or_b32_e32 v14, v10, v107
	v_lshrrev_b32_e32 v10, 8, v11
	v_or_b32_e32 v19, s74, v18
	v_add_u32_e32 v26, 0xc0, v70
	s_add_i32 s26, s73, 20
	s_add_i32 s50, s73, 28
	s_mov_b32 s51, s27
	v_ashrrev_i32_e32 v3, 31, v2
	v_mul_i32_i24_e32 v10, 0x44, v10
	v_or_b32_e32 v22, v18, v107
	v_lshrrev_b32_e32 v18, 8, v19
	v_or_b32_e32 v27, s74, v26
	v_add_u32_e32 v34, 0x100, v70
	v_or_b32_e32 v6, v70, v107
	v_lshl_add_u64 v[4:5], v[2:3], 0, s[26:27]
	v_lshl_add_u64 v[2:3], v[2:3], 0, s[50:51]
	v_ashrrev_i32_e32 v11, 31, v10
	v_mul_i32_i24_e32 v18, 0x44, v18
	v_or_b32_e32 v30, v26, v107
	v_lshrrev_b32_e32 v26, 8, v27
	v_or_b32_e32 v35, s74, v34
	v_add_u32_e32 v42, 0x140, v70
	v_lshlrev_b64 v[4:5], 15, v[4:5]
	v_lshlrev_b32_e32 v6, 7, v6
	v_lshlrev_b64 v[2:3], 15, v[2:3]
	v_lshl_add_u64 v[12:13], v[10:11], 0, s[26:27]
	v_lshl_add_u64 v[10:11], v[10:11], 0, s[50:51]
	v_ashrrev_i32_e32 v19, 31, v18
	v_mul_i32_i24_e32 v26, 0x44, v26
	v_or_b32_e32 v38, v34, v107
	v_lshrrev_b32_e32 v34, 8, v35
	v_or_b32_e32 v43, s74, v42
	v_add_u32_e32 v50, 0x180, v70
	v_and_b32_e32 v58, 0x7f80, v6
	v_lshl_add_u64 v[4:5], s[38:39], 0, v[4:5]
	v_lshl_add_u64 v[2:3], s[38:39], 0, v[2:3]
	v_lshlrev_b64 v[12:13], 15, v[12:13]
	v_lshlrev_b32_e32 v14, 7, v14
	v_lshlrev_b64 v[10:11], 15, v[10:11]
	v_lshl_add_u64 v[20:21], v[18:19], 0, s[26:27]
	v_lshl_add_u64 v[18:19], v[18:19], 0, s[50:51]
	v_ashrrev_i32_e32 v27, 31, v26
	v_mul_i32_i24_e32 v34, 0x44, v34
	v_or_b32_e32 v46, v42, v107
	v_lshrrev_b32_e32 v42, 8, v43
	v_or_b32_e32 v51, s74, v50
	v_lshl_add_u64 v[4:5], v[4:5], 0, v[58:59]
	v_lshl_add_u64 v[2:3], v[2:3], 0, v[58:59]
	v_and_b32_e32 v58, 0x7f80, v14
	v_lshl_add_u64 v[12:13], s[38:39], 0, v[12:13]
	v_lshl_add_u64 v[10:11], s[38:39], 0, v[10:11]
	v_lshlrev_b64 v[20:21], 15, v[20:21]
	v_lshlrev_b32_e32 v22, 7, v22
; __device__ __forceinline__ size_t tmo(int row, int ct, int nct) { return ((size_t)(row >> 8) * nct + ct) * 32768 + (size_t)(row & 255) * 128; }
; __device__ __forceinline__ void attn_b_prefetch(const bf16* Z, const float* rpb, int unit, v4u (&kr)[9], v4u (&vr)[9], float (&tr)[2]) {
;     const int tid = threadIdx.x; const int rp = unit & 63, h = (unit >> 6) & 7, b = unit >> 9;
;     const size_t tok0 = (size_t)b * SEQ; const int R0 = clampi(2 * rp - 4, 0, 120);
; #pragma unroll
;     for (int k = 0; k < 9; ++k) { const int it = tid + k * NTHREADS; const int row = it >> 3, ch = it & 7, gr = R0 + (row >> 6);
;         kr[k] = (v4u){0u, 0u, 0u, 0u}; vr[k] = (v4u){0u, 0u, 0u, 0u};
;         if (gr < 128) { const int t = (int)tok0 + gr * 64 + (row & 63); kr[k] = *(const v4u*)((const unsigned char*)Z + tmo(t, Z_KB / 64 + h, ZLD / 64) + ch * 16); vr[k] = *(const v4u*)((const unsigned char*)Z + tmo(t, Z_VB / 64 + h, ZLD / 64) + ch * 16); } }
; #pragma unroll
;     for (int k = 0; k < 2; ++k) { const int it = tid + k * NTHREADS, e = it - 16, dr = e >> 5, dc = e & 31;
;         tr[k] = (it >= B_TREAL) ? -INFINITY : ((e >= 0 && dr < 15 && dc < 31) ? rpb[h * 465 + dr * 31 + dc] * LOG2E : 0.f); }
; }
	v_lshlrev_b64 v[18:19], 15, v[18:19]
	v_lshl_add_u64 v[28:29], v[26:27], 0, s[26:27]
	v_lshl_add_u64 v[26:27], v[26:27], 0, s[50:51]
	v_ashrrev_i32_e32 v35, 31, v34
	v_mul_i32_i24_e32 v42, 0x44, v42
	v_or_b32_e32 v54, v50, v107
	v_lshrrev_b32_e32 v50, 8, v51
	v_lshl_add_u64 v[12:13], v[12:13], 0, v[58:59]
	v_lshl_add_u64 v[10:11], v[10:11], 0, v[58:59]
	v_and_b32_e32 v58, 0x7f80, v22
	v_lshl_add_u64 v[20:21], s[38:39], 0, v[20:21]
	v_lshl_add_u64 v[18:19], s[38:39], 0, v[18:19]
	v_lshlrev_b64 v[28:29], 15, v[28:29]
	v_lshlrev_b32_e32 v30, 7, v30
	v_lshlrev_b64 v[26:27], 15, v[26:27]
	v_lshl_add_u64 v[36:37], v[34:35], 0, s[26:27]
	v_lshl_add_u64 v[34:35], v[34:35], 0, s[50:51]
	v_ashrrev_i32_e32 v43, 31, v42
	v_mul_i32_i24_e32 v50, 0x44, v50
	v_lshl_add_u64 v[20:21], v[20:21], 0, v[58:59]
	v_lshl_add_u64 v[18:19], v[18:19], 0, v[58:59]
	v_and_b32_e32 v58, 0x7f80, v30
	v_lshl_add_u64 v[28:29], s[38:39], 0, v[28:29]
	v_lshl_add_u64 v[26:27], s[38:39], 0, v[26:27]
	v_lshlrev_b64 v[36:37], 15, v[36:37]
	v_lshlrev_b32_e32 v38, 7, v38
	v_lshlrev_b64 v[34:35], 15, v[34:35]
	v_lshl_add_u64 v[44:45], v[42:43], 0, s[26:27]
	v_lshl_add_u64 v[42:43], v[42:43], 0, s[50:51]
	v_ashrrev_i32_e32 v51, 31, v50
	v_lshl_add_u64 v[28:29], v[28:29], 0, v[58:59]
	v_lshl_add_u64 v[26:27], v[26:27], 0, v[58:59]
	v_and_b32_e32 v58, 0x7f80, v38
	v_lshl_add_u64 v[36:37], s[38:39], 0, v[36:37]
	v_lshl_add_u64 v[34:35], s[38:39], 0, v[34:35]
	v_lshlrev_b64 v[44:45], 15, v[44:45]
	v_lshlrev_b32_e32 v46, 7, v46
	v_lshlrev_b64 v[42:43], 15, v[42:43]
	v_lshl_add_u64 v[52:53], v[50:51], 0, s[26:27]
	v_lshl_add_u64 v[50:51], v[50:51], 0, s[50:51]
	v_lshl_add_u64 v[36:37], v[36:37], 0, v[58:59]
	v_lshl_add_u64 v[34:35], v[34:35], 0, v[58:59]
	v_and_b32_e32 v58, 0x7f80, v46
	v_lshl_add_u64 v[44:45], s[38:39], 0, v[44:45]
	v_lshl_add_u64 v[42:43], s[38:39], 0, v[42:43]
	v_lshlrev_b64 v[52:53], 15, v[52:53]
	v_lshlrev_b32_e32 v54, 7, v54
	v_lshlrev_b64 v[50:51], 15, v[50:51]
	v_lshl_add_u64 v[44:45], v[44:45], 0, v[58:59]
	v_lshl_add_u64 v[42:43], v[42:43], 0, v[58:59]
	v_and_b32_e32 v58, 0x7f80, v54
	v_lshl_add_u64 v[52:53], s[38:39], 0, v[52:53]
	v_lshl_add_u64 v[50:51], s[38:39], 0, v[50:51]
	v_lshl_add_u64 v[52:53], v[52:53], 0, v[58:59]
	v_lshl_add_u64 v[50:51], v[50:51], 0, v[58:59]
	v_lshl_add_u64 v[4:5], v[4:5], 0, v[102:103]
	v_lshl_add_u64 v[6:7], v[2:3], 0, v[102:103]
	v_lshl_add_u64 v[12:13], v[12:13], 0, v[102:103]
	v_lshl_add_u64 v[14:15], v[10:11], 0, v[102:103]
	v_lshl_add_u64 v[20:21], v[20:21], 0, v[102:103]
	v_lshl_add_u64 v[22:23], v[18:19], 0, v[102:103]
	v_lshl_add_u64 v[28:29], v[28:29], 0, v[102:103]
	v_lshl_add_u64 v[30:31], v[26:27], 0, v[102:103]
	v_lshl_add_u64 v[36:37], v[36:37], 0, v[102:103]
	v_lshl_add_u64 v[38:39], v[34:35], 0, v[102:103]
	v_lshl_add_u64 v[44:45], v[44:45], 0, v[102:103]
	v_lshl_add_u64 v[46:47], v[42:43], 0, v[102:103]
	v_lshl_add_u64 v[52:53], v[52:53], 0, v[102:103]
	v_lshl_add_u64 v[54:55], v[50:51], 0, v[102:103]
	global_load_dwordx4 v[2:5], v[4:5], off
	s_nop 0
	global_load_dwordx4 v[6:9], v[6:7], off
	s_nop 0
	global_load_dwordx4 v[10:13], v[12:13], off
	s_nop 0
	global_load_dwordx4 v[14:17], v[14:15], off
	s_nop 0
	global_load_dwordx4 v[18:21], v[20:21], off
	s_nop 0
	global_load_dwordx4 v[22:25], v[22:23], off
	s_nop 0
	global_load_dwordx4 v[26:29], v[28:29], off
	s_nop 0
	global_load_dwordx4 v[30:33], v[30:31], off
	s_nop 0
	global_load_dwordx4 v[34:37], v[36:37], off
	s_nop 0
	global_load_dwordx4 v[38:41], v[38:39], off
	s_nop 0
	global_load_dwordx4 v[42:45], v[44:45], off
	s_nop 0
	global_load_dwordx4 v[46:49], v[46:47], off
	s_nop 0
	global_load_dwordx4 v[50:53], v[52:53], off
	s_nop 0
	global_load_dwordx4 v[54:57], v[54:55], off
	v_cmp_gt_u32_e32 vcc, s52, v60
	v_mov_b32_e32 v60, v59
	v_mov_b32_e32 v61, v59
	v_mov_b32_e32 v58, v59
	v_mov_b64_e32 v[64:65], v[60:61]
	v_mov_b64_e32 v[68:69], v[60:61]
	v_mov_b64_e32 v[62:63], v[58:59]
	v_mov_b64_e32 v[66:67], v[58:59]
	s_and_saveexec_b64 s[70:71], vcc
	s_cbranch_execz .LBB0_290
	v_add_u32_e32 v58, 0x1c0, v70
	v_or_b32_e32 v60, s74, v58
	v_lshrrev_b32_e32 v60, 8, v60
	v_mul_i32_i24_e32 v60, 0x44, v60
	v_ashrrev_i32_e32 v61, 31, v60
	v_or_b32_e32 v58, v58, v107
	v_lshl_add_u64 v[62:63], v[60:61], 0, s[26:27]
	v_lshlrev_b64 v[62:63], 15, v[62:63]
	v_lshlrev_b32_e32 v58, 7, v58
	v_lshl_add_u64 v[60:61], v[60:61], 0, s[50:51]
	v_and_b32_e32 v58, 0x7f80, v58
	v_lshl_add_u64 v[62:63], s[38:39], 0, v[62:63]
	v_lshlrev_b64 v[60:61], 15, v[60:61]
	v_lshl_add_u64 v[62:63], v[62:63], 0, v[58:59]
	v_lshl_add_u64 v[60:61], s[38:39], 0, v[60:61]
	v_lshl_add_u64 v[62:63], v[62:63], 0, v[102:103]
	v_lshl_add_u64 v[60:61], v[60:61], 0, v[58:59]
	v_lshl_add_u64 v[60:61], v[60:61], 0, v[102:103]
	global_load_dwordx4 v[66:69], v[62:63], off
	s_nop 0
	global_load_dwordx4 v[62:65], v[60:61], off
